# static priority raise for waves 4-7 during the stick-breaking phase
# speedup vs baseline: 1.0015x; 1.0015x over previous
; __device__ __forceinline__ int lane_now() { int l; asm volatile("v_mbcnt_lo_u32_b32 %0, -1, 0\n\tv_mbcnt_hi_u32_b32 %0, -1, %0" : "=v"(l)); return l; }
; __global__ void __launch_bounds__(NWAVES * 64, 2) hybrid_fwd(Args args) {
;     ...
;     if (IN(9)) {
;         const int lane9 = lane_now(); const int tid9 = wid * 64 + lane9;
;         for (int run = vcu; run < 256; run += G) {
;             const int bh = run >> 2; int res_lo = 1 << 30, res_hi = -1;
; #pragma unroll 1
;             for (int i = 7; i >= 0; --i) sb_unit(bh >> 4, bh & 15, (run & 3) * 8 + i, U, VT, Y, lds, wid, lane9, res_lo, res_hi);
.LBB0_716:
	s_cmp_lt_i32 s92, 10
	s_cselect_b64 s[0:1], -1, 0
	s_cmp_gt_i32 s93, 9
	s_cselect_b64 s[2:3], -1, 0
	s_and_b64 s[2:3], s[0:1], s[2:3]
	s_andn2_b64 vcc, exec, s[2:3]
	s_cbranch_vccnz .LBB0_742
	s_cmpk_gt_i32 s72, 0xff
	v_mbcnt_lo_u32_b32 v0, -1, 0
	v_mbcnt_hi_u32_b32 v0, -1, v0
	s_cbranch_scc1 .LBB0_742
	v_readlane_b32 s0, v252, 36
	s_cmp_lt_u32 s0, 4
	s_cbranch_scc1 .Lmy_p9_prio_skip
	s_setprio 1
.Lmy_p9_prio_skip:
	v_writelane_b32 v251, s96, 6
	v_writelane_b32 v252, s2, 37
	s_mov_b64 s[66:67], src_shared_base
	v_writelane_b32 v251, s97, 7
	v_writelane_b32 v251, s83, 8
	v_writelane_b32 v252, s3, 38
	v_writelane_b32 v251, s92, 9
	v_readlane_b32 s1, v252, 36
	s_lshl_b32 s0, s1, 5
	v_writelane_b32 v251, s93, 10
	v_writelane_b32 v251, s73, 14
	v_writelane_b32 v252, s0, 18
	v_writelane_b32 v251, s82, 13
	s_lshl_b32 s0, s1, 3
	v_writelane_b32 v251, s0, 23
	s_lshl_b32 s0, s1, 10
	s_add_i32 s84, s0, 0
	s_lshl_b32 s0, s1, 2
	s_add_i32 s0, s0, 0
	s_lshr_b32 s2, s82, 7
	s_add_i32 s66, s0, 0x21080
	s_add_u32 s0, s70, 0x6000f80
	v_writelane_b32 v251, s0, 26
	s_addc_u32 s0, s71, 0
	v_writelane_b32 v251, s0, 29
	s_lshl_b32 s0, s74, 4
	s_lshl_b32 s5, s72, 4
	v_writelane_b32 v251, s0, 30
	s_lshl_b32 s0, s1, 19
	v_writelane_b32 v251, s0, 24
	s_add_u32 s0, s70, 0xaba0800
	v_writelane_b32 v251, s0, 31
	v_writelane_b32 v251, s70, 11
	s_addc_u32 s0, s71, 0
	s_mov_b32 s73, 0
	v_writelane_b32 v251, s71, 12
	v_writelane_b32 v251, s0, 48
	s_add_i32 s0, s2, 28
	s_mov_b32 s94, s2
	v_writelane_b32 v251, s0, 50
	v_mov_b32_e32 v1, 0
	v_mov_b32_e32 v144, 0xffffbf80
	s_mov_b32 s93, 0x5040100
	v_mov_b64_e32 v[120:121], s[76:77]
	s_mov_b32 s68, 0xbf80bf80
	s_add_i32 s95, 0, 0x21080
	v_mov_b32_e32 v145, 0xff800000
	v_writelane_b32 v251, s85, 4
	s_branch .LBB0_720

; __global__ void __launch_bounds__(NWAVES * 64, 2) hybrid_fwd(Args args) {
;     ...
;         for (int run = vcu; run < 256; run += G) {
;             const int bh = run >> 2; int res_lo = 1 << 30, res_hi = -1;
; #pragma unroll 1
;             for (int i = 7; i >= 0; --i) sb_unit(bh >> 4, bh & 15, (run & 3) * 8 + i, U, VT, Y, lds, wid, lane9, res_lo, res_hi);
;         }
;     }
.LBB0_741:
	s_setprio 0
	v_readlane_b32 s70, v251, 11
	v_readlane_b32 s92, v251, 9
	v_readlane_b32 s96, v251, 6
	v_readlane_b32 s2, v252, 37
	v_readlane_b32 s73, v251, 14
	v_readlane_b32 s82, v251, 13
	v_readlane_b32 s71, v251, 12
	v_readlane_b32 s93, v251, 10
	v_readlane_b32 s83, v251, 8
	v_readlane_b32 s97, v251, 7
	v_readlane_b32 s3, v252, 38
